# out-projection GEMM: each K-loop iteration issues one 64-line touch load of the tile's residual rows (epilogue input) so the epilogue loads hit cache; vmcnt 8->9 on the three waits it floats across
# speedup vs baseline: 1.0162x; 1.0017x over previous
; #define PG8_STAGE(bufoff, gbase, voff) do { _Pragma("unroll") for (int _i = 0; _i < 2; ++_i) \
;         __builtin_amdgcn_global_load_lds((const unsigned*)((const char*)(gbase) + (voff)[_i]), (PG8_LAS unsigned*)(lds + (bufoff) + ldsw + _i * 8192), 16, 0, 0); } while (0)
; #define PG8_WAIT_V(n) asm volatile("s_waitcnt vmcnt(" #n ")" ::: "memory")
; #define PG8_BAR __builtin_amdgcn_s_barrier()
; template <class Epi, class Sched, bool ALIGN_EPI = false, bool SP2 = false>
; __device__ __forceinline__ void gemm_phase(PG8_LAS unsigned char* lds, const Gemm g, const Sched& S, const Epi& E) {
;     ...
;     for (int i = 0; i < 2; ++i) { int R, C; stage_rc(tid * 16 + i * 8192, R, C); const int Rb = Epi::PERM ? ((R & ~31) + perm32(R & 31)) : R;
;         voffA[i] = (unsigned)(R * K + C) * 2u; voffB[i] = (unsigned)(Rb * K + C) * 2u; }
;     const size_t kstep = (size_t)(BK * 2);
;     const size_t hstep = (size_t)HALF * K * 2;
;     const size_t tstep = 2 * hstep;
;     const unsigned ldsw = (unsigned)wid * 1024u;
;     const int aoff = lds_byte(wr * 64 + fr, fq * 8), boff = lds_byte(wc * 32 + fr, fq * 8);
;     ...
;         PG8_STAGE(PG8_SB(0, 0), cB, voffB); PG8_STAGE(PG8_SB(0, 1), cB + hstep, voffB); PG8_STAGE(PG8_SA(0, 0), cA, voffA); PG8_STAGE(PG8_SA(0, 1), cA + hstep, voffA);
;         if (wr == 1) PG8_BAR;
;         PG8_WAIT_V(2); PG8_BAR;
;         PG8_STAGE(PG8_SB(1, 0), cB + kstep, voffB); PG8_STAGE(PG8_SA(1, 0), cA + kstep, voffA); PG8_STAGE(PG8_SB(1, 1), cB + hstep + kstep, voffB);
;         PG8_WAIT_V(6); PG8_BAR;
.LBB0_808:
	s_mov_b64 s[6:7], 0x80
	s_and_b32 s12, s4, 3
	s_add_i32 m0, s42, 0x18000
	v_lshl_add_u64 v[6:7], v[6:7], 0, s[6:7]
	s_lshl_b32 s13, s3, 13
	s_lshl_b32 s14, s12, 12
	s_waitcnt vmcnt(2)
	s_barrier
	global_load_lds_dwordx4 v[6:7], off
	v_lshl_add_u64 v[4:5], v[4:5], 0, s[6:7]
	s_add_i32 m0, s42, 0x1a000
	s_add_i32 s47, s42, 0x8000
	s_add_i32 s48, s42, 0xa000
	global_load_lds_dwordx4 v[4:5], off
	v_lshl_add_u64 v[2:3], v[2:3], 0, s[6:7]
	s_mov_b32 m0, s47
	s_add_u32 s4, s26, 0x40080
	global_load_lds_dwordx4 v[2:3], off
	v_lshl_add_u64 v[0:1], v[0:1], 0, s[6:7]
	s_mov_b32 m0, s48
	s_addc_u32 s5, s27, 0
	global_load_lds_dwordx4 v[0:1], off
	s_add_i32 m0, s42, 0x1c000
	v_lshl_add_u64 v[0:1], s[4:5], 0, v[148:149]
	global_load_lds_dwordx4 v[0:1], off
	v_lshl_add_u64 v[0:1], s[4:5], 0, v[144:145]
	s_add_i32 m0, s42, 0x1e000
	s_sext_i32_i8 s23, s2
	global_load_lds_dwordx4 v[0:1], off
	v_bfe_u32 v0, v230, 4, 2
	v_and_b32_e32 v1, 15, v230
	v_lshlrev_b32_e32 v3, 4, v0
	v_lshlrev_b32_e32 v5, 6, v230
	s_movk_i32 s2, 0x3c0
	v_lshl_or_b32 v170, s3, 6, v1
	v_lshlrev_b32_e32 v2, 3, v0
	v_lshl_or_b32 v1, v1, 6, v3
	v_and_or_b32 v3, v5, s2, v3
	v_cmp_eq_u32_e64 s[2:3], 0, v0
	v_lshlrev_b32_e32 v0, 8, v230
	v_lshl_or_b32 v172, s12, 5, v2
	v_and_b32_e32 v0, 0x38000, v0
	v_lshlrev_b32_e32 v2, 11, v11
	s_ashr_i32 s49, s11, 31
	s_lshl_b32 s4, s12, 2
	v_or3_b32 v0, v9, v0, v2
	s_add_u32 s4, s58, s4
	v_add_u32_e32 v152, v0, v10
	v_lshlrev_b32_e32 v0, 4, v8
	v_lshlrev_b32_e32 v4, 2, v230
	s_addc_u32 s5, s59, 0
	v_and_b32_e32 v0, 0x78000, v0
	v_and_b32_e32 v4, 32, v4
	s_waitcnt vmcnt(6)
	s_add_u32 s50, s4, 0x1e000000
	v_or3_b32 v0, v9, v0, v2
	v_bitop3_b32 v1, v1, s13, v4 bitop3:0xde
	v_bitop3_b32 v171, s14, v3, v4 bitop3:0xf6
	s_addc_u32 s51, s5, 0
	v_add_u32_e32 v154, v0, v10
	s_add_i32 s52, 0, 0x10000
	s_add_i32 s53, 0, 0x14000
	v_mbcnt_lo_u32_b32 v0, -1, 0
	v_mov_b32_e32 v153, v149
	v_mov_b32_e32 v155, v149
	v_mov_b64_e32 v[156:157], 0x300
	v_mov_b64_e32 v[158:159], 0x2ff
	v_add_u32_e32 v173, s52, v171
	v_add_u32_e32 v174, s53, v171
	v_add_u32_e32 v175, 0, v1
	v_mbcnt_hi_u32_b32 v176, -1, v0
	s_barrier
	v_lshlrev_b32_e32 v231, 12, v170
	v_and_b32_e32 v232, 0x60, v172
	v_lshl_add_u32 v231, v232, 2, v231
	v_bfe_u32 v232, v172, 3, 1
	v_lshl_add_u32 v231, v232, 9, v231
	v_bfe_u32 v232, v172, 4, 1
	v_lshl_add_u32 v231, v232, 16, v231
	s_branch .LBB0_810

; #define PG8_STAGE(bufoff, gbase, voff) do { _Pragma("unroll") for (int _i = 0; _i < 2; ++_i) \
;         __builtin_amdgcn_global_load_lds((const unsigned*)((const char*)(gbase) + (voff)[_i]), (PG8_LAS unsigned*)(lds + (bufoff) + ldsw + _i * 8192), 16, 0, 0); } while (0)
; #define PG8_LDA(dst, b, h) do { _Pragma("unroll") for (int m = 0; m < 4; ++m) _Pragma("unroll") for (int k = 0; k < 2; ++k) dst[m][k] = *(const PG8_LAS bf16x8*)(lds + PG8_SA(b, h) + aoff + m * 2048 + k * 1024); } while (0)
; #define PG8_LDB(dst, b, h) do { _Pragma("unroll") for (int n = 0; n < 2; ++n) _Pragma("unroll") for (int k = 0; k < 2; ++k) dst[n][k] = *(const PG8_LAS bf16x8*)(lds + PG8_SB(b, h) + boff + n * 2048 + k * 1024); } while (0)
; #define PG8_MMA(ai, bj, At, Bt) do { __builtin_amdgcn_s_setprio(1); _Pragma("unroll") for (int m = 0; m < 4; ++m) _Pragma("unroll") for (int n = 0; n < 2; ++n) _Pragma("unroll") for (int k = 0; k < 2; ++k) \
;         acc[ai][bj][m][n] = __builtin_amdgcn_mfma_f32_16x16x32_bf16(Bt[n][k], At[m][k], acc[ai][bj][m][n], 0, 0, 0); __builtin_amdgcn_s_setprio(0); } while (0)
; #define PG8_WAIT_V(n) asm volatile("s_waitcnt vmcnt(" #n ")" ::: "memory")
; #define PG8_WAIT_L(n) asm volatile("s_waitcnt lgkmcnt(" #n ")" ::: "memory")
; #define PG8_BAR __builtin_amdgcn_s_barrier()
; #define PG8_SCHED __builtin_amdgcn_sched_barrier(0)
; template <class Epi, class Sched, bool ALIGN_EPI = false, bool SP2 = false>
; __device__ __forceinline__ void gemm_phase(PG8_LAS unsigned char* lds, const Gemm g, const Sched& S, const Epi& E) {
;     ...
;             PG8_LDB(B0, 0, 0); PG8_LDB(B1, 0, 1); PG8_SCHED; PG8_LDA(At, 0, 0); PG8_STAGE(PG8_SA(1, 1), a1 + hstep, voffA);
;             PG8_WAIT_V(8); PG8_WAIT_L(0); PG8_BAR; PG8_MMA(0, 0, At, B0); PG8_MMA(0, 1, At, B1); PG8_BAR; PG8_SCHED;
;             PG8_LDA(At, 0, 1); PG8_STAGE(PG8_SB(0, 0), b2, voffB); PG8_STAGE(PG8_SB(0, 1), b2 + hstep, voffB); PG8_STAGE(PG8_SA(0, 0), a2, voffA);
.LBB0_813:
	ds_read_b128 v[128:131], v173
	ds_read_b128 v[132:135], v173 offset:1024
	ds_read_b128 v[136:139], v173 offset:2048
	ds_read_b128 v[140:143], v173 offset:3072
	ds_read_b128 v[160:163], v174
	ds_read_b128 v[164:167], v174 offset:1024
	ds_read_b128 v[178:181], v174 offset:2048
	ds_read_b128 v[182:185], v174 offset:3072
	s_add_u32 s26, s24, 0xfffc0080
	s_addc_u32 s27, s25, -1
	s_cmp_eq_u32 s70, 12
	s_cselect_b32 s37, s15, s27
	s_cselect_b32 s36, s60, s26
	s_cselect_b32 s27, s13, s69
	s_cselect_b32 s26, s61, s68
	v_lshl_add_u64 v[168:169], s[24:25], 0, v[152:153]
	s_add_i32 m0, s42, 0xc000
	ds_read_b128 v[186:189], v175
	ds_read_b128 v[190:193], v175 offset:1024
	ds_read_b128 v[194:197], v175 offset:2048
	ds_read_b128 v[198:201], v175 offset:3072
	ds_read_b128 v[202:205], v175 offset:4096
	ds_read_b128 v[206:209], v175 offset:5120
	ds_read_b128 v[210:213], v175 offset:6144
	ds_read_b128 v[214:217], v175 offset:7168
	global_load_lds_dwordx4 v[168:169], off
	v_lshl_add_u64 v[168:169], s[24:25], 0, v[154:155]
	s_add_i32 m0, s42, 0xe000
	s_nop 0
	global_load_lds_dwordx4 v[168:169], off
	s_add_i32 s98, s70, 2
	s_bfe_u32 s98, s98, 0x20001
	s_lshl_b32 s99, s98, 17
	s_lshr_b32 s98, s98, 1
	s_lshl_b32 s98, s98, 18
	s_add_i32 s99, s99, s98
	s_lshl_b32 s98, s22, 20
	s_add_i32 s99, s99, s98
	s_lshl_b32 s98, s23, 10
	s_add_i32 s99, s99, s98
	v_add_u32_e32 v232, s99, v231
	global_load_dword v233, v232, s[56:57]
	s_waitcnt vmcnt(9)
	s_waitcnt lgkmcnt(0)
	s_barrier
	s_setprio 1
	s_waitcnt lgkmcnt(0)
	v_mfma_f32_16x16x32_bf16 v[124:127], v[128:131], v[186:189], v[124:127]
	v_mfma_f32_16x16x32_bf16 v[120:123], v[136:139], v[186:189], v[120:123]
	v_mfma_f32_16x16x32_bf16 v[108:111], v[128:131], v[194:197], v[108:111]
	v_mfma_f32_16x16x32_bf16 v[104:107], v[136:139], v[194:197], v[104:107]
	v_mfma_f32_16x16x32_bf16 v[92:95], v[128:131], v[202:205], v[92:95]
	v_mfma_f32_16x16x32_bf16 v[88:91], v[136:139], v[202:205], v[88:91]
	v_mfma_f32_16x16x32_bf16 v[76:79], v[128:131], v[210:213], v[76:79]
	v_mfma_f32_16x16x32_bf16 v[72:75], v[136:139], v[210:213], v[72:75]
	v_mfma_f32_16x16x32_bf16 v[124:127], v[132:135], v[190:193], v[124:127]
	v_mfma_f32_16x16x32_bf16 v[120:123], v[140:143], v[190:193], v[120:123]
	v_mfma_f32_16x16x32_bf16 v[108:111], v[132:135], v[198:201], v[108:111]
	v_mfma_f32_16x16x32_bf16 v[104:107], v[140:143], v[198:201], v[104:107]
	v_mfma_f32_16x16x32_bf16 v[92:95], v[132:135], v[206:209], v[92:95]
	v_mfma_f32_16x16x32_bf16 v[88:91], v[140:143], v[206:209], v[88:91]
	v_mfma_f32_16x16x32_bf16 v[76:79], v[132:135], v[214:217], v[76:79]
	v_mfma_f32_16x16x32_bf16 v[72:75], v[140:143], v[214:217], v[72:75]
	s_setprio 0
	s_setprio 1
	v_mfma_f32_16x16x32_bf16 v[116:119], v[160:163], v[186:189], v[116:119]
	v_mfma_f32_16x16x32_bf16 v[112:115], v[178:181], v[186:189], v[112:115]
	v_mfma_f32_16x16x32_bf16 v[100:103], v[160:163], v[194:197], v[100:103]
	v_mfma_f32_16x16x32_bf16 v[96:99], v[178:181], v[194:197], v[96:99]
	v_mfma_f32_16x16x32_bf16 v[84:87], v[160:163], v[202:205], v[84:87]
	v_mfma_f32_16x16x32_bf16 v[80:83], v[178:181], v[202:205], v[80:83]
	v_mfma_f32_16x16x32_bf16 v[68:71], v[160:163], v[210:213], v[68:71]
	v_mfma_f32_16x16x32_bf16 v[64:67], v[178:181], v[210:213], v[64:67]
	v_mfma_f32_16x16x32_bf16 v[116:119], v[164:167], v[190:193], v[116:119]
	v_mfma_f32_16x16x32_bf16 v[112:115], v[182:185], v[190:193], v[112:115]
	v_mfma_f32_16x16x32_bf16 v[100:103], v[164:167], v[198:201], v[100:103]
	v_mfma_f32_16x16x32_bf16 v[96:99], v[182:185], v[198:201], v[96:99]
	v_mfma_f32_16x16x32_bf16 v[84:87], v[164:167], v[206:209], v[84:87]
	v_mfma_f32_16x16x32_bf16 v[80:83], v[182:185], v[206:209], v[80:83]
	v_mfma_f32_16x16x32_bf16 v[68:71], v[164:167], v[214:217], v[68:71]
	v_mfma_f32_16x16x32_bf16 v[64:67], v[182:185], v[214:217], v[64:67]
	s_setprio 0
	s_barrier
	s_add_i32 s71, s52, s39
	v_lshl_add_u64 v[168:169], s[26:27], 0, v[148:149]
	s_mov_b32 m0, s71
	ds_read_b128 v[186:189], v175 offset:16384
	ds_read_b128 v[190:193], v175 offset:17408
	ds_read_b128 v[194:197], v175 offset:18432
	ds_read_b128 v[198:201], v175 offset:19456
	ds_read_b128 v[202:205], v175 offset:20480
	ds_read_b128 v[206:209], v175 offset:21504
	ds_read_b128 v[210:213], v175 offset:22528
	ds_read_b128 v[214:217], v175 offset:23552
	global_load_lds_dwordx4 v[168:169], off
	s_add_i32 m0, s71, 0x2000
	s_add_u32 s72, s26, 0x40000
	v_lshl_add_u64 v[218:219], s[26:27], 0, v[144:145]
	s_addc_u32 s73, s27, 0
	s_add_i32 s71, s53, s39
	global_load_lds_dwordx4 v[218:219], off
	v_lshl_add_u64 v[220:221], s[72:73], 0, v[148:149]
	s_mov_b32 m0, s71
	v_lshl_add_u64 v[222:223], s[36:37], 0, v[146:147]
	global_load_lds_dwordx4 v[220:221], off
	v_lshl_add_u64 v[220:221], s[72:73], 0, v[144:145]
	s_add_i32 m0, s71, 0x2000
	s_nop 0
	global_load_lds_dwordx4 v[220:221], off
	v_lshl_add_u64 v[220:221], s[36:37], 0, v[150:151]
	s_mov_b32 m0, s42
	s_nop 0
	global_load_lds_dwordx4 v[220:221], off
	s_mov_b32 m0, s43
	s_nop 0
	global_load_lds_dwordx4 v[222:223], off
	s_waitcnt vmcnt(9)
	s_waitcnt lgkmcnt(0)
	s_barrier
; #define PG8_STAGE(bufoff, gbase, voff) do { _Pragma("unroll") for (int _i = 0; _i < 2; ++_i) \
;         __builtin_amdgcn_global_load_lds((const unsigned*)((const char*)(gbase) + (voff)[_i]), (PG8_LAS unsigned*)(lds + (bufoff) + ldsw + _i * 8192), 16, 0, 0); } while (0)
; #define PG8_LDA(dst, b, h) do { _Pragma("unroll") for (int m = 0; m < 4; ++m) _Pragma("unroll") for (int k = 0; k < 2; ++k) dst[m][k] = *(const PG8_LAS bf16x8*)(lds + PG8_SA(b, h) + aoff + m * 2048 + k * 1024); } while (0)
; #define PG8_LDB(dst, b, h) do { _Pragma("unroll") for (int n = 0; n < 2; ++n) _Pragma("unroll") for (int k = 0; k < 2; ++k) dst[n][k] = *(const PG8_LAS bf16x8*)(lds + PG8_SB(b, h) + boff + n * 2048 + k * 1024); } while (0)
; #define PG8_MMA(ai, bj, At, Bt) do { __builtin_amdgcn_s_setprio(1); _Pragma("unroll") for (int m = 0; m < 4; ++m) _Pragma("unroll") for (int n = 0; n < 2; ++n) _Pragma("unroll") for (int k = 0; k < 2; ++k) \
;         acc[ai][bj][m][n] = __builtin_amdgcn_mfma_f32_16x16x32_bf16(Bt[n][k], At[m][k], acc[ai][bj][m][n], 0, 0, 0); __builtin_amdgcn_s_setprio(0); } while (0)
; #define PG8_WAIT_V(n) asm volatile("s_waitcnt vmcnt(" #n ")" ::: "memory")
; #define PG8_WAIT_L(n) asm volatile("s_waitcnt lgkmcnt(" #n ")" ::: "memory")
; #define PG8_BAR __builtin_amdgcn_s_barrier()
; #define PG8_SCHED __builtin_amdgcn_sched_barrier(0)
; template <class Epi, class Sched, bool ALIGN_EPI = false, bool SP2 = false>
; __device__ __forceinline__ void gemm_phase(PG8_LAS unsigned char* lds, const Gemm g, const Sched& S, const Epi& E) {
;     ...
;             PG8_WAIT_V(8); PG8_WAIT_L(0); PG8_BAR; PG8_MMA(1, 0, At, B0); PG8_MMA(1, 1, At, B1); PG8_BAR; PG8_SCHED;
;             PG8_LDB(B0, 1, 0); PG8_LDB(B1, 1, 1); PG8_SCHED; PG8_LDA(At, 1, 0); PG8_STAGE(PG8_SA(0, 1), a2 + hstep, voffA);
;             PG8_WAIT_V(8); PG8_WAIT_L(0); PG8_BAR; PG8_MMA(0, 0, At, B0); PG8_MMA(0, 1, At, B1); PG8_BAR; PG8_SCHED;
	s_setprio 1
	s_waitcnt lgkmcnt(0)
	v_mfma_f32_16x16x32_bf16 v[60:63], v[128:131], v[186:189], v[60:63]
	v_mfma_f32_16x16x32_bf16 v[56:59], v[136:139], v[186:189], v[56:59]
	v_mfma_f32_16x16x32_bf16 v[44:47], v[128:131], v[194:197], v[44:47]
	v_mfma_f32_16x16x32_bf16 v[40:43], v[136:139], v[194:197], v[40:43]
	v_mfma_f32_16x16x32_bf16 v[28:31], v[128:131], v[202:205], v[28:31]
	v_mfma_f32_16x16x32_bf16 v[24:27], v[136:139], v[202:205], v[24:27]
	v_mfma_f32_16x16x32_bf16 v[12:15], v[128:131], v[210:213], v[12:15]
	v_mfma_f32_16x16x32_bf16 v[8:11], v[136:139], v[210:213], v[8:11]
	v_mfma_f32_16x16x32_bf16 v[60:63], v[132:135], v[190:193], v[60:63]
	v_mfma_f32_16x16x32_bf16 v[56:59], v[140:143], v[190:193], v[56:59]
	v_mfma_f32_16x16x32_bf16 v[44:47], v[132:135], v[198:201], v[44:47]
	v_mfma_f32_16x16x32_bf16 v[40:43], v[140:143], v[198:201], v[40:43]
	v_mfma_f32_16x16x32_bf16 v[28:31], v[132:135], v[206:209], v[28:31]
	v_mfma_f32_16x16x32_bf16 v[24:27], v[140:143], v[206:209], v[24:27]
	v_mfma_f32_16x16x32_bf16 v[12:15], v[132:135], v[214:217], v[12:15]
	v_mfma_f32_16x16x32_bf16 v[8:11], v[140:143], v[214:217], v[8:11]
	s_setprio 0
	s_setprio 1
	v_mfma_f32_16x16x32_bf16 v[52:55], v[160:163], v[186:189], v[52:55]
	v_mfma_f32_16x16x32_bf16 v[48:51], v[178:181], v[186:189], v[48:51]
	v_mfma_f32_16x16x32_bf16 v[36:39], v[160:163], v[194:197], v[36:39]
	v_mfma_f32_16x16x32_bf16 v[32:35], v[178:181], v[194:197], v[32:35]
	v_mfma_f32_16x16x32_bf16 v[20:23], v[160:163], v[202:205], v[20:23]
	v_mfma_f32_16x16x32_bf16 v[16:19], v[178:181], v[202:205], v[16:19]
	v_mfma_f32_16x16x32_bf16 v[4:7], v[160:163], v[210:213], v[4:7]
	v_mfma_f32_16x16x32_bf16 v[0:3], v[178:181], v[210:213], v[0:3]
	v_mfma_f32_16x16x32_bf16 v[52:55], v[164:167], v[190:193], v[52:55]
	v_mfma_f32_16x16x32_bf16 v[48:51], v[182:185], v[190:193], v[48:51]
	v_mfma_f32_16x16x32_bf16 v[36:39], v[164:167], v[198:201], v[36:39]
	v_mfma_f32_16x16x32_bf16 v[32:35], v[182:185], v[198:201], v[32:35]
	v_mfma_f32_16x16x32_bf16 v[20:23], v[164:167], v[206:209], v[20:23]
	v_mfma_f32_16x16x32_bf16 v[16:19], v[182:185], v[206:209], v[16:19]
	v_mfma_f32_16x16x32_bf16 v[4:7], v[164:167], v[214:217], v[4:7]
	v_mfma_f32_16x16x32_bf16 v[0:3], v[182:185], v[214:217], v[0:3]
	s_setprio 0
	s_barrier
	s_add_i32 s71, 0, 0x18000
	s_add_i32 s72, 0, 0x1c000
	v_add_u32_e32 v140, s71, v171
	v_add_u32_e32 v177, s72, v171
	ds_read_b128 v[128:131], v140
	ds_read_b128 v[132:135], v140 offset:1024
	ds_read_b128 v[136:139], v140 offset:2048
	ds_read_b128 v[140:143], v140 offset:3072
	ds_read_b128 v[160:163], v177
	ds_read_b128 v[164:167], v177 offset:1024
	ds_read_b128 v[178:181], v177 offset:2048
	ds_read_b128 v[182:185], v177 offset:3072
	s_add_u32 s36, s36, 0x40000
	s_addc_u32 s37, s37, 0
	s_mov_b32 m0, s44
	v_lshl_add_u64 v[224:225], s[36:37], 0, v[150:151]
	ds_read_b128 v[186:189], v175 offset:32768
	ds_read_b128 v[190:193], v175 offset:33792
	ds_read_b128 v[194:197], v175 offset:34816
	ds_read_b128 v[198:201], v175 offset:35840
	ds_read_b128 v[202:205], v175 offset:36864
	ds_read_b128 v[206:209], v175 offset:37888
	ds_read_b128 v[210:213], v175 offset:38912
	ds_read_b128 v[214:217], v175 offset:39936
	global_load_lds_dwordx4 v[224:225], off
	v_lshl_add_u64 v[224:225], s[36:37], 0, v[146:147]
	s_mov_b32 m0, s45
	s_nop 0
	global_load_lds_dwordx4 v[224:225], off
	s_waitcnt vmcnt(9)
	s_waitcnt lgkmcnt(0)
	s_barrier
	s_setprio 1
	s_waitcnt lgkmcnt(0)
	v_mfma_f32_16x16x32_bf16 v[124:127], v[128:131], v[186:189], v[124:127]
	v_mfma_f32_16x16x32_bf16 v[120:123], v[136:139], v[186:189], v[120:123]
	v_mfma_f32_16x16x32_bf16 v[108:111], v[128:131], v[194:197], v[108:111]
	v_mfma_f32_16x16x32_bf16 v[104:107], v[136:139], v[194:197], v[104:107]
	v_mfma_f32_16x16x32_bf16 v[92:95], v[128:131], v[202:205], v[92:95]
	v_mfma_f32_16x16x32_bf16 v[88:91], v[136:139], v[202:205], v[88:91]
	v_mfma_f32_16x16x32_bf16 v[76:79], v[128:131], v[210:213], v[76:79]
	v_mfma_f32_16x16x32_bf16 v[72:75], v[136:139], v[210:213], v[72:75]
	v_mfma_f32_16x16x32_bf16 v[124:127], v[132:135], v[190:193], v[124:127]
	v_mfma_f32_16x16x32_bf16 v[120:123], v[140:143], v[190:193], v[120:123]
	v_mfma_f32_16x16x32_bf16 v[108:111], v[132:135], v[198:201], v[108:111]
	v_mfma_f32_16x16x32_bf16 v[104:107], v[140:143], v[198:201], v[104:107]
	v_mfma_f32_16x16x32_bf16 v[92:95], v[132:135], v[206:209], v[92:95]
	v_mfma_f32_16x16x32_bf16 v[88:91], v[140:143], v[206:209], v[88:91]
	v_mfma_f32_16x16x32_bf16 v[76:79], v[132:135], v[214:217], v[76:79]
	v_mfma_f32_16x16x32_bf16 v[72:75], v[140:143], v[214:217], v[72:75]
	s_setprio 0
	s_setprio 1
	v_mfma_f32_16x16x32_bf16 v[116:119], v[160:163], v[186:189], v[116:119]
	v_mfma_f32_16x16x32_bf16 v[112:115], v[178:181], v[186:189], v[112:115]
	v_mfma_f32_16x16x32_bf16 v[100:103], v[160:163], v[194:197], v[100:103]
	v_mfma_f32_16x16x32_bf16 v[96:99], v[178:181], v[194:197], v[96:99]
	v_mfma_f32_16x16x32_bf16 v[84:87], v[160:163], v[202:205], v[84:87]
	v_mfma_f32_16x16x32_bf16 v[80:83], v[178:181], v[202:205], v[80:83]
	v_mfma_f32_16x16x32_bf16 v[68:71], v[160:163], v[210:213], v[68:71]
	v_mfma_f32_16x16x32_bf16 v[64:67], v[178:181], v[210:213], v[64:67]
	v_mfma_f32_16x16x32_bf16 v[116:119], v[164:167], v[190:193], v[116:119]
	v_mfma_f32_16x16x32_bf16 v[112:115], v[182:185], v[190:193], v[112:115]
	v_mfma_f32_16x16x32_bf16 v[100:103], v[164:167], v[198:201], v[100:103]
	v_mfma_f32_16x16x32_bf16 v[96:99], v[182:185], v[198:201], v[96:99]
	v_mfma_f32_16x16x32_bf16 v[84:87], v[164:167], v[206:209], v[84:87]
	v_mfma_f32_16x16x32_bf16 v[80:83], v[182:185], v[206:209], v[80:83]
	v_mfma_f32_16x16x32_bf16 v[68:71], v[164:167], v[214:217], v[68:71]
	v_mfma_f32_16x16x32_bf16 v[64:67], v[182:185], v[214:217], v[64:67]
	s_setprio 0
	s_barrier
; #define PG8_STAGE(bufoff, gbase, voff) do { _Pragma("unroll") for (int _i = 0; _i < 2; ++_i) \
;         __builtin_amdgcn_global_load_lds((const unsigned*)((const char*)(gbase) + (voff)[_i]), (PG8_LAS unsigned*)(lds + (bufoff) + ldsw + _i * 8192), 16, 0, 0); } while (0)
; #define PG8_LDA(dst, b, h) do { _Pragma("unroll") for (int m = 0; m < 4; ++m) _Pragma("unroll") for (int k = 0; k < 2; ++k) dst[m][k] = *(const PG8_LAS bf16x8*)(lds + PG8_SA(b, h) + aoff + m * 2048 + k * 1024); } while (0)
; #define PG8_MMA(ai, bj, At, Bt) do { __builtin_amdgcn_s_setprio(1); _Pragma("unroll") for (int m = 0; m < 4; ++m) _Pragma("unroll") for (int n = 0; n < 2; ++n) _Pragma("unroll") for (int k = 0; k < 2; ++k) \
;         acc[ai][bj][m][n] = __builtin_amdgcn_mfma_f32_16x16x32_bf16(Bt[n][k], At[m][k], acc[ai][bj][m][n], 0, 0, 0); __builtin_amdgcn_s_setprio(0); } while (0)
; #define PG8_WAIT_V(n) asm volatile("s_waitcnt vmcnt(" #n ")" ::: "memory")
; #define PG8_WAIT_L(n) asm volatile("s_waitcnt lgkmcnt(" #n ")" ::: "memory")
; #define PG8_BAR __builtin_amdgcn_s_barrier()
; #define PG8_SCHED __builtin_amdgcn_sched_barrier(0)
; template <class Epi, class Sched, bool ALIGN_EPI = false, bool SP2 = false>
; __device__ __forceinline__ void gemm_phase(PG8_LAS unsigned char* lds, const Gemm g, const Sched& S, const Epi& E) {
;     ...
;             PG8_LDA(At, 1, 1); PG8_STAGE(PG8_SB(1, 0), b3, voffB); PG8_STAGE(PG8_SB(1, 1), b3 + hstep, voffB); PG8_STAGE(PG8_SA(1, 0), a3, voffA);
;             PG8_WAIT_V(8); PG8_WAIT_L(0); PG8_BAR; PG8_MMA(1, 0, At, B0); PG8_MMA(1, 1, At, B1); PG8_BAR; PG8_SCHED;
	s_add_i32 s36, s71, s39
	v_lshl_add_u64 v[168:169], v[168:169], 0, s[6:7]
	s_mov_b32 m0, s36
	ds_read_b128 v[186:189], v175 offset:49152
	ds_read_b128 v[190:193], v175 offset:50176
	ds_read_b128 v[194:197], v175 offset:51200
	ds_read_b128 v[198:201], v175 offset:52224
	ds_read_b128 v[202:205], v175 offset:53248
	ds_read_b128 v[206:209], v175 offset:54272
	ds_read_b128 v[210:213], v175 offset:55296
	ds_read_b128 v[214:217], v175 offset:56320
	global_load_lds_dwordx4 v[168:169], off
	s_add_i32 m0, s36, 0x2000
	s_add_u32 s26, s26, 0x40080
	v_lshl_add_u64 v[168:169], v[218:219], 0, s[6:7]
	s_addc_u32 s27, s27, 0
	s_add_i32 s36, s72, s39
	global_load_lds_dwordx4 v[168:169], off
	v_lshl_add_u64 v[168:169], s[26:27], 0, v[148:149]
	s_mov_b32 m0, s36
	s_nop 0
	global_load_lds_dwordx4 v[168:169], off
	v_lshl_add_u64 v[168:169], s[26:27], 0, v[144:145]
	s_add_i32 m0, s36, 0x2000
	s_nop 0
	global_load_lds_dwordx4 v[168:169], off
	v_lshl_add_u64 v[168:169], v[220:221], 0, s[6:7]
	s_mov_b32 m0, s47
	s_nop 0
	global_load_lds_dwordx4 v[168:169], off
	v_lshl_add_u64 v[168:169], v[222:223], 0, s[6:7]
	s_mov_b32 m0, s48
	s_nop 0
	global_load_lds_dwordx4 v[168:169], off
	s_waitcnt vmcnt(8)
	s_waitcnt lgkmcnt(0)
	s_barrier
	s_setprio 1
	s_waitcnt lgkmcnt(0)
	v_mfma_f32_16x16x32_bf16 v[60:63], v[128:131], v[186:189], v[60:63]
	v_mfma_f32_16x16x32_bf16 v[56:59], v[136:139], v[186:189], v[56:59]
	v_mfma_f32_16x16x32_bf16 v[44:47], v[128:131], v[194:197], v[44:47]
	v_mfma_f32_16x16x32_bf16 v[40:43], v[136:139], v[194:197], v[40:43]
	v_mfma_f32_16x16x32_bf16 v[28:31], v[128:131], v[202:205], v[28:31]
	v_mfma_f32_16x16x32_bf16 v[24:27], v[136:139], v[202:205], v[24:27]
	v_mfma_f32_16x16x32_bf16 v[12:15], v[128:131], v[210:213], v[12:15]
	v_mfma_f32_16x16x32_bf16 v[8:11], v[136:139], v[210:213], v[8:11]
	v_mfma_f32_16x16x32_bf16 v[60:63], v[132:135], v[190:193], v[60:63]
	v_mfma_f32_16x16x32_bf16 v[56:59], v[140:143], v[190:193], v[56:59]
	v_mfma_f32_16x16x32_bf16 v[44:47], v[132:135], v[198:201], v[44:47]
	v_mfma_f32_16x16x32_bf16 v[40:43], v[140:143], v[198:201], v[40:43]
	v_mfma_f32_16x16x32_bf16 v[28:31], v[132:135], v[206:209], v[28:31]
	v_mfma_f32_16x16x32_bf16 v[24:27], v[140:143], v[206:209], v[24:27]
	v_mfma_f32_16x16x32_bf16 v[12:15], v[132:135], v[214:217], v[12:15]
	v_mfma_f32_16x16x32_bf16 v[8:11], v[140:143], v[214:217], v[8:11]
	s_setprio 0
	s_setprio 1
	v_mfma_f32_16x16x32_bf16 v[52:55], v[160:163], v[186:189], v[52:55]
	v_mfma_f32_16x16x32_bf16 v[48:51], v[178:181], v[186:189], v[48:51]
	v_mfma_f32_16x16x32_bf16 v[36:39], v[160:163], v[194:197], v[36:39]
	v_mfma_f32_16x16x32_bf16 v[32:35], v[178:181], v[194:197], v[32:35]
	v_mfma_f32_16x16x32_bf16 v[20:23], v[160:163], v[202:205], v[20:23]
	v_mfma_f32_16x16x32_bf16 v[16:19], v[178:181], v[202:205], v[16:19]
	v_mfma_f32_16x16x32_bf16 v[4:7], v[160:163], v[210:213], v[4:7]
	v_mfma_f32_16x16x32_bf16 v[0:3], v[178:181], v[210:213], v[0:3]
	v_mfma_f32_16x16x32_bf16 v[52:55], v[164:167], v[190:193], v[52:55]
	v_mfma_f32_16x16x32_bf16 v[48:51], v[182:185], v[190:193], v[48:51]
	v_mfma_f32_16x16x32_bf16 v[36:39], v[164:167], v[198:201], v[36:39]
	v_mfma_f32_16x16x32_bf16 v[32:35], v[182:185], v[198:201], v[32:35]
	v_mfma_f32_16x16x32_bf16 v[20:23], v[164:167], v[206:209], v[20:23]
	v_mfma_f32_16x16x32_bf16 v[16:19], v[182:185], v[206:209], v[16:19]
	v_mfma_f32_16x16x32_bf16 v[4:7], v[164:167], v[214:217], v[4:7]
	v_mfma_f32_16x16x32_bf16 v[0:3], v[182:185], v[214:217], v[0:3]
	s_setprio 0
	s_barrier
	s_add_i32 s70, s70, 2
	s_add_u32 s24, s24, 0x100
	s_addc_u32 s25, s25, 0
	s_add_u32 s68, s68, 0x100
	s_addc_u32 s69, s69, 0
	s_cmp_gt_u32 s70, 13
	s_cbranch_scc0 .LBB0_813
; __device__ __forceinline__ u32x2 pack4(f32x4 v) { u32x2 w; w.x = cvt_pk_bf16(v[0], v[1]); w.y = cvt_pk_bf16(v[2], v[3]); return w; }
;     __device__ __forceinline__ void operator()(const f32x4 (&acc)[2][2][4][2], const Unit& u, int wr, int wc, int fr, int fq) const {
;         const int row0 = u.pm * BM + wr * 64 + fr, col0 = u.pn * BM + wc * 32 + 8 * fq;
;         const float* base = (u.pm * BM < split) ? base0 : base1; bf16_t* const xn = (bf16_t*)(ws + WS_XN); float* const ssq = (float*)(ws + WS_SSQ);
; #pragma unroll
;         for (int ai = 0; ai < 2; ++ai)
; #pragma unroll
;         for (int mh = 0; mh < 4; mh += 2) {
;             f32x4 pre[4][2][2];
; #pragma unroll
;             for (int m = mh; m < mh + 2; ++m)
; #pragma unroll
;                 for (int bj = 0; bj < 2; ++bj)
; #pragma unroll
;                     for (int n = 0; n < 2; ++n) pre[m][bj][n] = *(const f32x4*)(base + (size_t)(row0 + ai * HALF + m * 16) * 1024 + col0 + bj * HALF + n * 4);
;             asm volatile("" ::: "memory");
; #pragma unroll
;             for (int m = mh; m < mh + 2; ++m) { const int row = row0 + ai * HALF + m * 16; const size_t off = (size_t)row * 1024 + col0; float ss = 0.f;
; #pragma unroll
;                 for (int bj = 0; bj < 2; ++bj) { u32x4e w;
; #pragma unroll
;                     for (int n = 0; n < 2; ++n) { const f32x4 o = pre[m][bj][n] + acc[ai][bj][m][n] * s;
;                         *(f32x4*)(out + off + bj * HALF + n * 4) = o;
;                         if (NORMOUT) { const u32x2 p = pack4(o); w[2 * n] = p.x; w[2 * n + 1] = p.y; ss += (o[0] * o[0] + o[1] * o[1]) + (o[2] * o[2] + o[3] * o[3]); } }
;                     if (NORMOUT) *(u32x4e*)(xn + off + bj * HALF) = w; }
;                 if (NORMOUT) { ss += __shfl_xor(ss, 16); ss += __shfl_xor(ss, 32); if (fq == 0) ssq[(size_t)row * 16 + u.pn * 4 + wc] = ss; } }
	v_lshl_add_u32 v164, s22, 8, v170
	v_lshl_or_b32 v160, s23, 8, v172
	v_ashrrev_i32_e32 v161, 31, v160
	v_ashrrev_i32_e32 v165, 31, v164
	v_lshl_add_u64 v[162:163], v[160:161], 2, s[56:57]
	v_lshlrev_b64 v[128:129], 12, v[164:165]
	v_lshl_add_u64 v[196:197], v[162:163], 0, v[128:129]
	global_load_dwordx4 v[180:183], v[196:197], off
	global_load_dwordx4 v[184:187], v[196:197], off offset:16
	global_load_dwordx4 v[188:191], v[196:197], off offset:512
	global_load_dwordx4 v[192:195], v[196:197], off offset:528
	v_or_b32_e32 v166, 16, v164
	v_ashrrev_i32_e32 v167, 31, v166
	v_lshlrev_b64 v[128:129], 12, v[166:167]
	v_lshl_add_u64 v[168:169], v[162:163], 0, v[128:129]
	global_load_dwordx4 v[136:139], v[168:169], off offset:16
	global_load_dwordx4 v[140:143], v[168:169], off
	global_load_dwordx4 v[128:131], v[168:169], off offset:528
	global_load_dwordx4 v[132:135], v[168:169], off offset:512
	v_and_b32_e32 v178, 64, v176
	v_xor_b32_e32 v177, 16, v176
	v_add_u32_e32 v178, 64, v178
	v_xor_b32_e32 v179, 32, v176
	v_cmp_lt_i32_e32 vcc, v177, v178
	v_lshlrev_b64 v[198:199], 10, v[164:165]
	v_lshl_add_u64 v[198:199], v[198:199], 0, v[160:161]
	v_cndmask_b32_e32 v177, v176, v177, vcc
	v_cmp_lt_i32_e32 vcc, v179, v178
	v_lshlrev_b32_e32 v178, 2, v177
	v_lshl_add_u64 v[198:199], v[198:199], 1, s[64:65]
	v_cndmask_b32_e32 v179, v176, v179, vcc
	v_lshlrev_b32_e32 v177, 2, v179
	s_lshl_b32 s22, s23, 2
	s_ashr_i32 s23, s22, 31
	s_lshl_b64 s[22:23], s[22:23], 2
	s_add_u32 s22, s50, s22
	s_addc_u32 s23, s51, s23
	s_waitcnt vmcnt(0)
	v_pk_add_f32 v[126:127], v[182:183], v[126:127]
	v_pk_add_f32 v[124:125], v[180:181], v[124:125]
	v_pk_add_f32 v[122:123], v[186:187], v[122:123]
	v_pk_add_f32 v[120:121], v[184:185], v[120:121]
	v_pk_add_f32 v[118:119], v[190:191], v[118:119]
	v_pk_add_f32 v[116:117], v[188:189], v[116:117]
	v_pk_add_f32 v[182:183], v[194:195], v[114:115]
	v_pk_add_f32 v[180:181], v[192:193], v[112:113]
	global_store_dwordx4 v[196:197], v[124:127], off
	v_cvt_pk_bf16_f32 v112, v124, v125
	v_cvt_pk_bf16_f32 v113, v126, v127
	v_mul_f32_e32 v125, v125, v125
	v_mul_f32_e32 v127, v127, v127
	global_store_dwordx4 v[196:197], v[120:123], off offset:16
	v_cvt_pk_bf16_f32 v114, v120, v121
	v_cvt_pk_bf16_f32 v115, v122, v123
	v_mul_f32_e32 v121, v121, v121
	v_mul_f32_e32 v123, v123, v123
	v_mul_f32_e32 v179, v117, v117
	v_mul_f32_e32 v184, v119, v119
	v_fmac_f32_e32 v125, v124, v124
	v_fmac_f32_e32 v127, v126, v126
	v_fmac_f32_e32 v121, v120, v120
	v_fmac_f32_e32 v123, v122, v122
	v_mul_f32_e32 v185, v181, v181
	v_mul_f32_e32 v186, v183, v183
	v_fmac_f32_e32 v179, v116, v116
	v_fmac_f32_e32 v184, v118, v118
	v_add_f32_e32 v120, v125, v127
	v_add_f32_e32 v121, v121, v123
	v_fmac_f32_e32 v185, v180, v180
	v_fmac_f32_e32 v186, v182, v182
	v_add_f32_e32 v122, v179, v184
	v_add_f32_e32 v120, v120, v121
	v_add_f32_e32 v120, v122, v120
	v_add_f32_e32 v121, v185, v186
	v_add_f32_e32 v120, v121, v120
	ds_bpermute_b32 v121, v178, v120
	global_store_dwordx4 v[198:199], v[112:115], off
	global_store_dwordx4 v[196:197], v[116:119], off offset:512
	global_store_dwordx4 v[196:197], v[180:183], off offset:528
	v_cvt_pk_bf16_f32 v114, v116, v117
	v_cvt_pk_bf16_f32 v115, v118, v119
	s_waitcnt lgkmcnt(0)
	v_add_f32_e32 v112, v120, v121
	ds_bpermute_b32 v113, v177, v112
	v_cvt_pk_bf16_f32 v116, v180, v181
	v_cvt_pk_bf16_f32 v117, v182, v183
	global_store_dwordx4 v[198:199], v[114:117], off offset:256
	s_and_saveexec_b64 s[24:25], s[2:3]
	s_cbranch_execz .LBB0_816
	v_lshlrev_b64 v[114:115], 6, v[164:165]
	v_lshl_add_u64 v[114:115], s[22:23], 0, v[114:115]
	s_waitcnt lgkmcnt(0)
	v_add_f32_e32 v112, v112, v113
	global_store_dword v[114:115], v112, off

; __global__ void __launch_bounds__(NWAVES * 64, 2) mega_fwd(Args args) {
	.amdhsa_kernel _Z8mega_fwd4Args
		.amdhsa_group_segment_fixed_size 0
		.amdhsa_private_segment_fixed_size 0
		.amdhsa_kernarg_size 424
		.amdhsa_user_sgpr_count 2
		.amdhsa_user_sgpr_dispatch_ptr 0
		.amdhsa_user_sgpr_queue_ptr 0
		.amdhsa_user_sgpr_kernarg_segment_ptr 1
		.amdhsa_user_sgpr_dispatch_id 0
		.amdhsa_user_sgpr_kernarg_preload_length 0
		.amdhsa_user_sgpr_kernarg_preload_offset 0
		.amdhsa_user_sgpr_private_segment_size 0
		.amdhsa_uses_dynamic_stack 0
		.amdhsa_enable_private_segment 0
		.amdhsa_system_sgpr_workgroup_id_x 1
		.amdhsa_system_sgpr_workgroup_id_y 0
		.amdhsa_system_sgpr_workgroup_id_z 0
		.amdhsa_system_sgpr_workgroup_info 0
		.amdhsa_system_vgpr_workitem_id 2
		.amdhsa_next_free_vgpr 256
		.amdhsa_next_free_sgpr 100
		.amdhsa_accum_offset 256
		.amdhsa_reserve_vcc 1
		.amdhsa_float_round_mode_32 0
		.amdhsa_float_round_mode_16_64 0
		.amdhsa_float_denorm_mode_32 3
		.amdhsa_float_denorm_mode_16_64 3
		.amdhsa_dx10_clamp 1
		.amdhsa_ieee_mode 1
		.amdhsa_fp16_overflow 0
		.amdhsa_tg_split 0
		.amdhsa_exception_fp_ieee_invalid_op 0
		.amdhsa_exception_fp_denorm_src 0
		.amdhsa_exception_fp_ieee_div_zero 0
		.amdhsa_exception_fp_ieee_overflow 0
		.amdhsa_exception_fp_ieee_underflow 0
		.amdhsa_exception_fp_ieee_inexact 0
		.amdhsa_exception_int_div_zero 0
	.end_amdhsa_kernel
